# DeltaNet tasks run at wave priority 0 instead of 2 (chunkwise form is no longer the longest dependent chain)
# speedup vs baseline: 1.0114x; 1.0114x over previous
; __device__ __forceinline__ void dn_task(const Params& p, int l, int task, char* smem) {
;     ...
;   const float* cw = p.in[11] + (size_t)l * 5 * 768;
;   const float Aexp = __expf(p.in[12][l * 8 + dir * 4 + hd]);
;   const float dtb = p.in[13][l * 8 + dir * 4 + hd];
;   bf16_t* O = WS_BF(p, OFF_SC) + (size_t)dir * NTOK * 256;
;   const int v = vh * 32 + (tid >> 3), kq = tid & 7;
;   for (int i = tid; i < 5 * 192; i += 256) {
;     const int j = i / 192, c = i - j * 192;
;     wl[i] = cw[j * 768 + (c >> 6) * 256 + hd * 64 + (c & 63)];
.LBB0_161:
	s_mov_b64 s[30:31], s[82:83]
	s_andn2_b64 vcc, exec, s[40:41]
	s_cbranch_vccnz .LBB0_105
	s_setprio 0
	s_and_b32 s54, s60, 1
	s_lshl_b32 s56, s54, 2
	v_readlane_b32 s2, v250, 38
	s_bfe_u32 s55, s60, 0x20001
	s_or_b32 s40, s56, s2
	s_or_b32 s40, s40, s55
	s_lshl_b32 s40, s40, 2
	v_mov_b32_e32 v0, s40
	s_load_dwordx16 s[36:51], s[0:1], 0x58
	v_mov_b32_e32 v138, v172
	s_waitcnt lgkmcnt(0)
	global_load_dword v6, v0, s[38:39]
	global_load_dword v160, v0, s[40:41]
	s_movk_i32 s40, 0x3c0
	v_cmp_gt_i32_e32 vcc, s40, v138
	s_lshl_b32 s61, s55, 6
	s_and_saveexec_b64 s[40:41], vcc
	s_cbranch_execz .LBB0_179
	v_max_i32_e32 v0, 0x2c0, v138
	v_sub_u32_e32 v0, v0, v138
	s_waitcnt vmcnt(0)
	v_add_u32_e32 v2, 0xff, v0
	s_movk_i32 s42, 0xff
	v_and_b32_e32 v4, 63, v138
	v_cmp_lt_u32_e32 vcc, s42, v2
	s_mov_b64 s[44:45], 0
	s_and_saveexec_b64 s[42:43], vcc
	s_xor_b64 s[42:43], exec, s[42:43]
	s_cbranch_execnz .LBB0_173
	s_andn2_saveexec_b64 s[42:43], s[42:43]
	s_cbranch_execnz .LBB0_176
